# GEMV loops (modulation, shift@W): all weight rows of an item requested up front (scratch loads) so the 4-deep loop hits cache
# speedup vs baseline: 1.0278x; 1.0010x over previous
.LBB0_51:
	s_or_b64 exec, exec, s[8:9]
	s_mul_hi_i32 s8, s18, 0x2aaaaaab
	s_lshr_b32 s9, s8, 31
	s_ashr_i32 s19, s8, 4
	s_add_i32 s19, s19, s9
	s_mul_i32 s8, s19, 0x60
	s_sub_i32 s8, s18, s8
	s_lshl_b32 s8, s8, 6
	s_ashr_i32 s9, s8, 31
	s_mul_i32 s21, s19, 0x1800000
	s_lshl_b64 s[10:11], s[8:9], 2
	s_mul_hi_i32 s20, s19, 0x1800000
	s_add_u32 s10, s21, s10
	s_addc_u32 s11, s20, s11
	v_mov_b32_e32 v16, 0
	v_lshl_add_u64 v[14:15], v[10:11], 0, s[10:11]
	s_mov_b64 s[10:11], 0
	v_mov_b32_e32 v12, v1
	s_mov_b32 s98, 0
	s_mov_b32 s99, 0
.Lpf0_loop:
	v_lshl_add_u64 v[250:251], v[14:15], 0, s[98:99]
	global_load_dword v249, v[250:251], off
	s_add_u32 s98, s98, 0x6000
	s_cmp_lg_u32 s98, 0x300000
	s_cbranch_scc1 .Lpf0_loop
	v_mov_b32_e32 v17, v16
	v_mov_b32_e32 v18, v16
	v_mov_b32_e32 v19, v16
	v_mov_b32_e32 v20, v16
	v_mov_b32_e32 v21, v16
	v_mov_b32_e32 v22, v16
	v_mov_b32_e32 v23, v16
	v_mov_b32_e32 v24, v16
	s_waitcnt lgkmcnt(0)
	s_barrier

.LBB0_122:
	s_or_b64 exec, exec, s[54:55]
	s_ashr_i32 s35, s34, 31
	s_lshl_b64 s[40:41], s[34:35], 2
	s_add_u32 s40, s44, s40
	s_addc_u32 s41, s45, s41
	v_mov_b64_e32 v[18:19], s[40:41]
	v_mul_lo_u32 v14, v6, s39
	v_mul_lo_u32 v15, v7, s38
	v_mad_u64_u32 v[12:13], s[40:41], v6, s38, v[18:19]
	v_add3_u32 v13, v15, v13, v14
	v_mul_lo_u32 v16, v8, s39
	v_mul_lo_u32 v17, v9, s38
	v_mad_u64_u32 v[14:15], s[42:43], v8, s38, v[18:19]
	v_add3_u32 v15, v17, v15, v16
	v_mul_lo_u32 v20, v10, s39
	v_mul_lo_u32 v21, v11, s38
	v_mad_u64_u32 v[16:17], s[42:43], v10, s38, v[18:19]
	s_lshl_b64 s[40:41], s[38:39], 4
	v_add3_u32 v17, v21, v17, v20
	v_mul_lo_u32 v20, v4, s39
	v_mul_lo_u32 v21, v5, s38
	v_mad_u64_u32 v[18:19], s[38:39], v4, s38, v[18:19]
	v_add3_u32 v19, v21, v19, v20
	v_lshl_add_u64 v[244:245], v[12:13], 0, v[2:3]
	v_lshl_add_u64 v[246:247], v[14:15], 0, v[2:3]
	v_lshl_add_u64 v[248:249], v[16:17], 0, v[2:3]
	v_lshl_add_u64 v[250:251], v[18:19], 0, v[2:3]
	s_mov_b32 s98, 0
.Lpf1_loop:
	global_load_dword v252, v[244:245], off
	global_load_dword v252, v[246:247], off
	global_load_dword v252, v[248:249], off
	global_load_dword v252, v[250:251], off
	v_lshl_add_u64 v[244:245], v[244:245], 0, s[40:41]
	v_lshl_add_u64 v[246:247], v[246:247], 0, s[40:41]
	v_lshl_add_u64 v[248:249], v[248:249], 0, s[40:41]
	v_lshl_add_u64 v[250:251], v[250:251], 0, s[40:41]
	s_add_u32 s98, s98, 1
	s_cmp_lg_u32 s98, 32
	s_cbranch_scc1 .Lpf1_loop
	v_mov_b32_e32 v20, 0
	s_mov_b32 s35, 0
	v_mov_b32_e32 v21, v20
	v_mov_b32_e32 v22, v20
	v_mov_b32_e32 v23, v20
	v_mov_b32_e32 v24, v20
	v_mov_b32_e32 v25, v20
	v_mov_b32_e32 v26, v20
	v_mov_b32_e32 v27, v20
	v_mov_b32_e32 v39, v20
	s_waitcnt lgkmcnt(0)
	s_barrier
